# mix-phase deferred modulation GEMV: 7 of 8 serialized weight loads per iteration hoisted to the loop top (copy-in, counted waits)
# baseline (speedup 1.0000x reference)
; __device__ void mod_phase(int tid_, int bid_, int nblk_, const Params& p, char* smem, int item0, int item1) {
;     ...
; #pragma unroll 8
;     for (int k = kg * 128; k < kg * 128 + 128; ++k) {
;       float4 w4 = *(const float4*)(W + (size_t)k * 6144 + col);
; #pragma unroll
;       for (int r = 0; r < 5; ++r) {
;         float s = sC[r * 2048 + k];
;         acc[r][0] += s * w4.x; acc[r][1] += s * w4.y; acc[r][2] += s * w4.z; acc[r][3] += s * w4.w;
;       }
;     }
.LBB0_597:
	v_lshl_add_u64 v[28:29], v[26:27], 0, s[20:21]
	ds_read_b128 v[30:33], v1
	ds_read_b128 v[22:25], v1 offset:16
	global_load_dwordx4 v[34:37], v[28:29], off
	v_add_co_u32_e32 v236, vcc, s3, v28
	s_nop 1
	v_addc_co_u32_e32 v237, vcc, 0, v29, vcc
	global_load_dwordx4 v[236:239], v[236:237], off
	v_add_co_u32_e32 v240, vcc, s97, v28
	s_nop 1
	v_addc_co_u32_e32 v241, vcc, 0, v29, vcc
	global_load_dwordx4 v[240:243], v[240:241], off
	v_add_co_u32_e32 v244, vcc, s83, v28
	s_nop 1
	v_addc_co_u32_e32 v245, vcc, 0, v29, vcc
	global_load_dwordx4 v[244:247], v[244:245], off
	v_add_co_u32_e32 v248, vcc, s82, v28
	s_nop 1
	v_addc_co_u32_e32 v249, vcc, 0, v29, vcc
	global_load_dwordx4 v[248:251], v[248:249], off
	v_add_co_u32_e32 v210, vcc, s92, v28
	s_nop 1
	v_addc_co_u32_e32 v211, vcc, 0, v29, vcc
	global_load_dwordx4 v[210:213], v[210:211], off
	v_add_co_u32_e32 v214, vcc, s91, v28
	s_nop 1
	v_addc_co_u32_e32 v215, vcc, 0, v29, vcc
	global_load_dwordx4 v[214:217], v[214:215], off
	v_add_co_u32_e32 v218, vcc, s85, v28
	s_nop 1
	v_addc_co_u32_e32 v219, vcc, 0, v29, vcc
	global_load_dwordx4 v[218:221], v[218:219], off
	s_add_u32 s20, s20, 0x30000
	s_addc_u32 s21, s21, 0
	s_cmp_lg_u32 s20, 0x300000
	s_waitcnt vmcnt(7) lgkmcnt(1)
	v_pk_fma_f32 v[38:39], v[34:35], v[30:31], v[18:19] op_sel_hi:[1,0,1]
	v_pk_fma_f32 v[162:163], v[36:37], v[30:31], v[20:21] op_sel_hi:[1,0,1]
	ds_read_b128 v[18:21], v1 offset:8192
	s_waitcnt lgkmcnt(0)
	v_pk_fma_f32 v[164:165], v[34:35], v[18:19], v[14:15] op_sel_hi:[1,0,1]
	v_pk_fma_f32 v[166:167], v[36:37], v[18:19], v[16:17] op_sel_hi:[1,0,1]
	ds_read_b128 v[14:17], v1 offset:16384
	s_waitcnt lgkmcnt(0)
	v_pk_fma_f32 v[168:169], v[34:35], v[14:15], v[10:11] op_sel_hi:[1,0,1]
	v_pk_fma_f32 v[170:171], v[36:37], v[14:15], v[12:13] op_sel_hi:[1,0,1]
	ds_read_b128 v[10:13], v1 offset:24576
	s_waitcnt lgkmcnt(0)
	v_pk_fma_f32 v[172:173], v[34:35], v[10:11], v[6:7] op_sel_hi:[1,0,1]
	v_pk_fma_f32 v[174:175], v[36:37], v[10:11], v[8:9] op_sel_hi:[1,0,1]
	ds_read_b128 v[6:9], v1 offset:32768
	s_waitcnt lgkmcnt(0)
	v_pk_fma_f32 v[34:35], v[34:35], v[6:7], v[2:3] op_sel_hi:[1,0,1]
	v_add_co_u32_e32 v2, vcc, s3, v28
	v_pk_fma_f32 v[36:37], v[36:37], v[6:7], v[4:5] op_sel_hi:[1,0,1]
	s_nop 0
	v_addc_co_u32_e32 v3, vcc, 0, v29, vcc
	s_waitcnt vmcnt(6)
	v_mov_b32_e32 v2, v236
	v_mov_b32_e32 v3, v237
	v_mov_b32_e32 v4, v238
	v_mov_b32_e32 v5, v239
	v_pk_fma_f32 v[38:39], v[2:3], v[30:31], v[38:39] op_sel:[0,1,0]
	v_pk_fma_f32 v[30:31], v[4:5], v[30:31], v[162:163] op_sel:[0,1,0]
	v_pk_fma_f32 v[162:163], v[2:3], v[18:19], v[164:165] op_sel:[0,1,0]
	v_pk_fma_f32 v[18:19], v[4:5], v[18:19], v[166:167] op_sel:[0,1,0]
	v_pk_fma_f32 v[164:165], v[2:3], v[14:15], v[168:169] op_sel:[0,1,0]
	v_pk_fma_f32 v[166:167], v[2:3], v[10:11], v[172:173] op_sel:[0,1,0]
	v_pk_fma_f32 v[34:35], v[2:3], v[6:7], v[34:35] op_sel:[0,1,0]
	v_add_co_u32_e32 v2, vcc, s97, v28
	v_pk_fma_f32 v[14:15], v[4:5], v[14:15], v[170:171] op_sel:[0,1,0]
	s_nop 0
	v_addc_co_u32_e32 v3, vcc, 0, v29, vcc
	v_pk_fma_f32 v[10:11], v[4:5], v[10:11], v[174:175] op_sel:[0,1,0]
	v_pk_fma_f32 v[6:7], v[4:5], v[6:7], v[36:37] op_sel:[0,1,0]
	s_waitcnt vmcnt(5)
	v_mov_b32_e32 v2, v240
	v_mov_b32_e32 v3, v241
	v_mov_b32_e32 v4, v242
	v_mov_b32_e32 v5, v243
	v_pk_fma_f32 v[36:37], v[2:3], v[32:33], v[38:39] op_sel_hi:[1,0,1]
	v_pk_fma_f32 v[38:39], v[2:3], v[20:21], v[162:163] op_sel_hi:[1,0,1]
	v_pk_fma_f32 v[162:163], v[2:3], v[16:17], v[164:165] op_sel_hi:[1,0,1]
	v_pk_fma_f32 v[164:165], v[2:3], v[12:13], v[166:167] op_sel_hi:[1,0,1]
	v_pk_fma_f32 v[34:35], v[2:3], v[8:9], v[34:35] op_sel_hi:[1,0,1]
	v_add_co_u32_e32 v2, vcc, s83, v28
	v_pk_fma_f32 v[30:31], v[4:5], v[32:33], v[30:31] op_sel_hi:[1,0,1]
	s_nop 0
	v_addc_co_u32_e32 v3, vcc, 0, v29, vcc
	v_pk_fma_f32 v[18:19], v[4:5], v[20:21], v[18:19] op_sel_hi:[1,0,1]
	v_pk_fma_f32 v[14:15], v[4:5], v[16:17], v[14:15] op_sel_hi:[1,0,1]
	v_pk_fma_f32 v[10:11], v[4:5], v[12:13], v[10:11] op_sel_hi:[1,0,1]
	v_pk_fma_f32 v[6:7], v[4:5], v[8:9], v[6:7] op_sel_hi:[1,0,1]
	s_waitcnt vmcnt(4)
	v_mov_b32_e32 v2, v244
	v_mov_b32_e32 v3, v245
	v_mov_b32_e32 v4, v246
	v_mov_b32_e32 v5, v247
	v_mov_b32_e32 v8, v33
	v_pk_fma_f32 v[32:33], v[2:3], v[8:9], v[36:37] op_sel_hi:[1,0,1]
	v_pk_fma_f32 v[30:31], v[4:5], v[8:9], v[30:31] op_sel_hi:[1,0,1]
	v_mov_b32_e32 v8, v21
	v_pk_fma_f32 v[20:21], v[2:3], v[8:9], v[38:39] op_sel_hi:[1,0,1]
	v_pk_fma_f32 v[18:19], v[4:5], v[8:9], v[18:19] op_sel_hi:[1,0,1]
	v_mov_b32_e32 v8, v17
	v_pk_fma_f32 v[16:17], v[2:3], v[8:9], v[162:163] op_sel_hi:[1,0,1]
	v_pk_fma_f32 v[14:15], v[4:5], v[8:9], v[14:15] op_sel_hi:[1,0,1]
	v_mov_b32_e32 v8, v13
	v_pk_fma_f32 v[36:37], v[2:3], v[8:9], v[164:165] op_sel_hi:[1,0,1]
	v_pk_fma_f32 v[38:39], v[4:5], v[8:9], v[10:11] op_sel_hi:[1,0,1]
	v_mov_b32_e32 v8, v9
	v_pk_fma_f32 v[162:163], v[2:3], v[8:9], v[34:35] op_sel_hi:[1,0,1]
	v_add_co_u32_e32 v2, vcc, s82, v28
	v_pk_fma_f32 v[164:165], v[4:5], v[8:9], v[6:7] op_sel_hi:[1,0,1]
	s_nop 0
	v_addc_co_u32_e32 v3, vcc, 0, v29, vcc
	s_waitcnt vmcnt(3)
; __device__ void mod_phase(int tid_, int bid_, int nblk_, const Params& p, char* smem, int item0, int item1) {
;     ...
; #pragma unroll 8
;     for (int k = kg * 128; k < kg * 128 + 128; ++k) {
;       float4 w4 = *(const float4*)(W + (size_t)k * 6144 + col);
; #pragma unroll
;       for (int r = 0; r < 5; ++r) {
;         float s = sC[r * 2048 + k];
;         acc[r][0] += s * w4.x; acc[r][1] += s * w4.y; acc[r][2] += s * w4.z; acc[r][3] += s * w4.w;
;       }
;     }
; #pragma unroll
;     for (int r = 0; r < 5; ++r)
; #pragma unroll
;       for (int e = 0; e < 4; ++e) sRed[(kg * 5 + r) * 64 + cl * 4 + e] = acc[r][e];
;     __syncthreads();
;     for (int o = tid; o < 320; o += 256) {
;       int r = o / 64, cc = o % 64;
;       float s = 0.f;
; #pragma unroll
;       for (int g = 0; g < 16; ++g) s += sRed[(g * 5 + r) * 64 + cc];
	v_mov_b32_e32 v2, v248
	v_mov_b32_e32 v3, v249
	v_mov_b32_e32 v4, v250
	v_mov_b32_e32 v5, v251
	ds_read_b128 v[10:13], v1 offset:16400
	ds_read_b128 v[6:9], v1 offset:8208
	v_pk_fma_f32 v[166:167], v[2:3], v[22:23], v[32:33] op_sel_hi:[1,0,1]
	v_pk_fma_f32 v[168:169], v[4:5], v[22:23], v[30:31] op_sel_hi:[1,0,1]
	ds_read_b128 v[30:33], v1 offset:24592
	s_waitcnt lgkmcnt(2)
	v_pk_fma_f32 v[16:17], v[2:3], v[10:11], v[16:17] op_sel_hi:[1,0,1]
	v_pk_fma_f32 v[14:15], v[4:5], v[10:11], v[14:15] op_sel_hi:[1,0,1]
	s_waitcnt lgkmcnt(0)
	v_pk_fma_f32 v[170:171], v[2:3], v[30:31], v[36:37] op_sel_hi:[1,0,1]
	ds_read_b128 v[34:37], v1 offset:32784
	v_pk_fma_f32 v[20:21], v[2:3], v[6:7], v[20:21] op_sel_hi:[1,0,1]
	v_pk_fma_f32 v[18:19], v[4:5], v[6:7], v[18:19] op_sel_hi:[1,0,1]
	v_pk_fma_f32 v[38:39], v[4:5], v[30:31], v[38:39] op_sel_hi:[1,0,1]
	v_add_u32_e32 v1, 32, v1
	s_waitcnt lgkmcnt(0)
	v_pk_fma_f32 v[162:163], v[2:3], v[34:35], v[162:163] op_sel_hi:[1,0,1]
	v_add_co_u32_e32 v2, vcc, s92, v28
	v_pk_fma_f32 v[164:165], v[4:5], v[34:35], v[164:165] op_sel_hi:[1,0,1]
	s_nop 0
	v_addc_co_u32_e32 v3, vcc, 0, v29, vcc
	s_waitcnt vmcnt(2)
	v_mov_b32_e32 v2, v210
	v_mov_b32_e32 v3, v211
	v_mov_b32_e32 v4, v212
	v_mov_b32_e32 v5, v213
	v_pk_fma_f32 v[166:167], v[2:3], v[22:23], v[166:167] op_sel:[0,1,0]
	v_pk_fma_f32 v[20:21], v[2:3], v[6:7], v[20:21] op_sel:[0,1,0]
	v_pk_fma_f32 v[6:7], v[4:5], v[6:7], v[18:19] op_sel:[0,1,0]
	v_pk_fma_f32 v[16:17], v[2:3], v[10:11], v[16:17] op_sel:[0,1,0]
	v_pk_fma_f32 v[10:11], v[4:5], v[10:11], v[14:15] op_sel:[0,1,0]
	v_pk_fma_f32 v[14:15], v[2:3], v[30:31], v[170:171] op_sel:[0,1,0]
	v_pk_fma_f32 v[18:19], v[4:5], v[30:31], v[38:39] op_sel:[0,1,0]
	v_pk_fma_f32 v[30:31], v[2:3], v[34:35], v[162:163] op_sel:[0,1,0]
	v_add_co_u32_e32 v2, vcc, s91, v28
	v_pk_fma_f32 v[22:23], v[4:5], v[22:23], v[168:169] op_sel:[0,1,0]
	s_nop 0
	v_addc_co_u32_e32 v3, vcc, 0, v29, vcc
	v_pk_fma_f32 v[34:35], v[4:5], v[34:35], v[164:165] op_sel:[0,1,0]
	s_waitcnt vmcnt(1)
	v_mov_b32_e32 v2, v214
	v_mov_b32_e32 v3, v215
	v_mov_b32_e32 v4, v216
	v_mov_b32_e32 v5, v217
	v_pk_fma_f32 v[38:39], v[2:3], v[24:25], v[166:167] op_sel_hi:[1,0,1]
	v_pk_fma_f32 v[162:163], v[2:3], v[8:9], v[20:21] op_sel_hi:[1,0,1]
	v_pk_fma_f32 v[164:165], v[2:3], v[12:13], v[16:17] op_sel_hi:[1,0,1]
	v_pk_fma_f32 v[168:169], v[2:3], v[32:33], v[14:15] op_sel_hi:[1,0,1]
	v_pk_fma_f32 v[30:31], v[2:3], v[36:37], v[30:31] op_sel_hi:[1,0,1]
	v_add_co_u32_e32 v2, vcc, s85, v28
	v_pk_fma_f32 v[22:23], v[4:5], v[24:25], v[22:23] op_sel_hi:[1,0,1]
	s_nop 0
	v_addc_co_u32_e32 v3, vcc, 0, v29, vcc
	v_pk_fma_f32 v[6:7], v[4:5], v[8:9], v[6:7] op_sel_hi:[1,0,1]
	v_pk_fma_f32 v[166:167], v[4:5], v[12:13], v[10:11] op_sel_hi:[1,0,1]
	v_pk_fma_f32 v[170:171], v[4:5], v[32:33], v[18:19] op_sel_hi:[1,0,1]
	v_pk_fma_f32 v[34:35], v[4:5], v[36:37], v[34:35] op_sel_hi:[1,0,1]
	s_waitcnt vmcnt(0)
	v_mov_b32_e32 v2, v218
	v_mov_b32_e32 v3, v219
	v_mov_b32_e32 v4, v220
	v_mov_b32_e32 v5, v221
	v_mov_b32_e32 v8, v25
	v_pk_fma_f32 v[18:19], v[2:3], v[8:9], v[38:39] op_sel_hi:[1,0,1]
	v_pk_fma_f32 v[20:21], v[4:5], v[8:9], v[22:23] op_sel_hi:[1,0,1]
	v_mov_b32_e32 v8, v9
	v_pk_fma_f32 v[14:15], v[2:3], v[8:9], v[162:163] op_sel_hi:[1,0,1]
	v_pk_fma_f32 v[16:17], v[4:5], v[8:9], v[6:7] op_sel_hi:[1,0,1]
	v_mov_b32_e32 v6, v13
	v_mov_b32_e32 v8, v33
	v_mov_b32_e32 v22, v37
	v_pk_fma_f32 v[10:11], v[2:3], v[6:7], v[164:165] op_sel_hi:[1,0,1]
	v_pk_fma_f32 v[12:13], v[4:5], v[6:7], v[166:167] op_sel_hi:[1,0,1]
	v_pk_fma_f32 v[6:7], v[2:3], v[8:9], v[168:169] op_sel_hi:[1,0,1]
	v_pk_fma_f32 v[8:9], v[4:5], v[8:9], v[170:171] op_sel_hi:[1,0,1]
	v_pk_fma_f32 v[2:3], v[2:3], v[22:23], v[30:31] op_sel_hi:[1,0,1]
	v_pk_fma_f32 v[4:5], v[4:5], v[22:23], v[34:35] op_sel_hi:[1,0,1]
	s_cbranch_scc1 .LBB0_597
	ds_write_b128 v188, v[18:21] offset:40960
	ds_write_b128 v188, v[14:17] offset:41216
	ds_write_b128 v188, v[10:13] offset:41472
	ds_write_b128 v188, v[6:9] offset:41728
	ds_write_b128 v188, v[2:5] offset:41984
	s_waitcnt lgkmcnt(0)
	s_barrier
	s_mov_b64 s[20:21], exec
	v_readlane_b32 s24, v255, 14
	v_readlane_b32 s25, v255, 15
	v_readlane_b32 s36, v252, 17
	s_and_b64 s[24:25], s[20:21], s[24:25]
	s_movk_i32 s26, 0x17c0
	v_readlane_b32 s46, v252, 27
	v_readlane_b32 s47, v252, 28
	v_readlane_b32 s37, v252, 18
	v_readlane_b32 s38, v252, 19
	v_readlane_b32 s39, v252, 20
	v_readlane_b32 s40, v252, 21
	v_readlane_b32 s41, v252, 22
	v_readlane_b32 s42, v252, 23
	v_readlane_b32 s43, v252, 24
	v_readlane_b32 s44, v252, 25
	v_readlane_b32 s45, v252, 26
	v_readlane_b32 s48, v252, 29
	v_readlane_b32 s49, v252, 30
	v_readlane_b32 s50, v252, 31
	v_readlane_b32 s51, v252, 32
	s_mov_b64 exec, s[24:25]
	s_cbranch_execz .LBB0_601
	s_mul_i32 s24, s0, 0x1800
	s_add_i32 s24, s24, s22
	s_mulk_i32 s0, 0x6000
	s_add_i32 s0, s0, s24
	s_mov_b64 s[22:23], 0
	v_mov_b32_e32 v1, v189
	v_mov_b32_e32 v2, v118
